# windowed attention: key tiles fully inside the window for every row of the wave (wave-wide min/max of the distance base tracked in SGPRs) skip the per-element window compare+select
# baseline (speedup 1.0000x reference)
;   DI u16* qbuf() const { return (u16*)(ws + OFF_qbuf); }
;   DI u16* kbuf() const { return (u16*)(ws + OFF_kbuf); }
;   DI u16* vtbuf() const { return (u16*)(ws + OFF_vtbuf); }
; #define tid_opaque() tid_from(WAVE_S)
; template <int MODE>
; DI void attn_item(const Params& p, int layer, int b, int hq, int qb, u16* lds, const int WAVE_S) {
;   const int tid = tid_opaque(), lane = tid & 63, wave = tid >> 6;
;   const int r = lane & 31, h = lane >> 5;
;   const int kvh = hq >> 2;
;   const int q0 = qb * 128 + wave * 32;
;   const u16* qp = p.qbuf() + (((size_t)(MODE * 32 + b) * 8 + hq) * SEQ + q0 + r) * 64;
;   const u16* kp = p.kbuf() + ((size_t)(MODE * 32 + b) * 2 + kvh) * SEQ * 64;
;   const u16* vp = p.vtbuf() + ((size_t)(MODE * 32 + b) * 2 + kvh) * 64 * SEQ;
;   bf16x8 qf[4];
; #pragma unroll
;   for (int ks = 0; ks < 4; ++ks) qf[ks] = *(const bf16x8*)(qp + ks * 16 + h * 8);
;   int t_begin, t_end, kbase0;
;   if (MODE == 0) { t_begin = 0; t_end = 32; kbase0 = 0; }
;   else { t_begin = (qb == 0) ? 2 : 0; t_end = (qb == 15) ? 4 : 6; kbase0 = qb * 128 - 128; }
;   float m_run, l_run;
;   float slope2 = 0.f;
;   if (MODE == 0) { m_run = 0.f; l_run = 0.f; }
;   else {
;     m_run = p.sink[layer * 8 + hq] * LOG2E;
;     l_run = (h == 0) ? 1.f : 0.f;
;     slope2 = exp2f(-(float)(hq + 1)) * LOG2E;
;   }
;   f32x16 negm;
; #pragma unroll
;   for (int i = 0; i < 16; ++i) negm[i] = -m_run;
;   f32x16 o[2];
; #pragma unroll
;   for (int dt = 0; dt < 2; ++dt)
; #pragma unroll
;     for (int i = 0; i < 16; ++i) o[dt][i] = 0.f;
;   const int lr = tid >> 3, lc = (tid & 7) * 8;
;   u32x4 kr[2], vr[2];
;   {
;     const int kb = kbase0 + t_begin * 64;
; #pragma unroll
;     for (int it = 0; it < 2; ++it) {
;       kr[it] = *(const u32x4*)(kp + (size_t)(kb + lr + 32 * it) * 64 + lc);
;       vr[it] = *(const u32x4*)(vp + (size_t)(lr + 32 * it) * SEQ + kb + lc);
;     }
;   }
; DI void phase_attn(const Params& p, int layer, u16* lds, const int WAVE_S) {
;     ...
;     const int it = next_item(ctr, WAVE_S);
;     if (it >= 1024) break;
;     const int mode = it >> 9, slot = it & 511;
;     const int grp = (slot >> 6) * 8 + xcd;
;     const int within = slot & 63;
;     const int b = grp >> 1, kvh = grp & 1;
;     const int hq = kvh * 4 + (within >> 4), qb = within & 15;
.LBB0_176:
	s_or_b64 exec, exec, s[18:19]
	s_waitcnt lgkmcnt(0)
	s_barrier
	ds_read_b32 v0, v1 offset:40976
	s_movk_i32 s18, 0x3ff
	s_waitcnt lgkmcnt(0)
	v_cmp_lt_i32_e32 vcc, s18, v0
	v_readfirstlane_b32 s28, v0
	s_mov_b64 s[18:19], -1
	s_cbranch_vccnz .LBB0_171
	s_lshr_b32 s18, s28, 3
	s_and_b32 s44, s18, 56
	s_or_b32 s18, s44, s17
	s_lshr_b32 s50, s18, 1
	s_bfe_u32 s18, s28, 0x20004
	v_readlane_b32 s19, v165, 55
	s_and_b32 s34, s28, 15
	s_or_b32 s49, s18, s19
	s_lshl_b32 s36, s34, 7
	s_cmpk_gt_u32 s28, 0x1ff
	s_mov_b64 s[18:19], -1
	s_cbranch_scc0 .LBB0_190
	v_mbcnt_lo_u32_b32 v3, -1, 0
	v_mbcnt_hi_u32_b32 v3, -1, v3
	s_or_b32 s18, s50, 32
	v_add_u32_e32 v6, s33, v3
	v_ashrrev_i32_e32 v10, 1, v6
	v_and_b32_e32 v0, 0xffffffe0, v10
	s_lshl_b32 s19, s18, 14
	s_lshl_b32 s28, s49, 11
	v_and_b32_e32 v114, 31, v3
	v_add_u32_e32 v116, s36, v0
	s_or_b32 s19, s19, s28
	v_ashrrev_i32_e32 v117, 31, v116
	v_or_b32_e32 v0, s19, v114
	s_lshl_b32 s18, s18, 19
	v_readlane_b32 s19, v166, 19
	v_lshl_add_u64 v[4:5], v[0:1], 0, v[116:117]
	v_readlane_b32 s52, v164, 51
	s_or_b32 s45, s19, s18
	v_readlane_b32 s18, v164, 49
	v_lshlrev_b64 v[4:5], 7, v[4:5]
	v_readlane_b32 s53, v164, 52
	v_readlane_b32 s19, v164, 50
	s_add_u32 s96, s18, s45
	v_lshl_add_u64 v[4:5], s[52:53], 0, v[4:5]
	s_addc_u32 s97, s19, 0
	v_readlane_b32 s52, v164, 25
	s_cmp_eq_u32 s34, 15
	v_readlane_b32 s18, v167, 1
	v_readlane_b32 s53, v164, 26
	v_readlane_b32 s54, v164, 27
	v_readlane_b32 s55, v164, 28
	v_readlane_b32 s56, v164, 29
	v_readlane_b32 s57, v164, 30
	v_readlane_b32 s58, v164, 31
	v_readlane_b32 s59, v164, 32
	v_readlane_b32 s60, v164, 33
	v_readlane_b32 s61, v164, 34
	s_cselect_b32 s51, 4, 6
	v_readlane_b32 s19, v167, 2
	s_or_b32 s28, s49, s18
	v_readlane_b32 s62, v164, 35
	v_readlane_b32 s63, v164, 36
	v_readlane_b32 s64, v164, 37
	v_readlane_b32 s65, v164, 38
	v_readlane_b32 s66, v164, 39
	v_readlane_b32 s67, v164, 40
	s_mov_b64 s[52:53], s[60:61]
	v_bfe_u32 v11, v3, 5, 1
	s_lshl_b64 s[18:19], s[28:29], 2
	s_mov_b64 s[56:57], s[64:65]
	v_lshlrev_b32_e32 v0, 4, v11
	s_add_u32 s18, s56, s18
	v_lshl_add_u64 v[4:5], v[4:5], 0, v[0:1]
	s_addc_u32 s19, s57, s19
	global_load_dwordx4 v[82:85], v[4:5], off
	global_load_dwordx4 v[86:89], v[4:5], off offset:32
	global_load_dwordx4 v[90:93], v[4:5], off offset:64
	global_load_dwordx4 v[94:97], v[4:5], off offset:96
	global_load_dword v2, v1, s[18:19]
	s_add_i32 s18, s49, 1
	v_cvt_f32_ubyte0_e32 v4, s18
	s_mov_b32 s18, 0x42fc0000
	v_cmp_lt_f32_e32 vcc, s18, v4
	v_mov_b32_e32 v5, 0x42800000
	s_and_b64 s[18:19], vcc, exec
	v_cndmask_b32_e32 v5, 0, v5, vcc
	v_sub_f32_e32 v4, v5, v4
	v_exp_f32_e32 v4, v4
	s_cselect_b32 s18, 0xffffffc0, 0
	s_cmp_eq_u32 s34, 0
	s_cselect_b32 s28, 2, 0
	v_ldexp_f32 v34, v4, s18
	v_readlane_b32 s18, v164, 53
	s_add_u32 s85, s18, s45
	v_readlane_b32 s18, v164, 54
	v_cmp_eq_u32_e64 s[34:35], 0, v11
	s_addc_u32 s98, s18, 0
	s_add_i32 s84, s36, 0xffffff80
	s_lshl_b32 s18, s28, 6
	v_cndmask_b32_e64 v129, 0, 1.0, s[34:35]
	v_ashrrev_i32_e32 v4, 3, v6
	s_add_i32 s34, s18, s84
	v_add_u32_e32 v6, s34, v4
	v_lshlrev_b32_e32 v5, 4, v3
	v_and_b32_e32 v28, 0x70, v5
	v_mov_b32_e32 v29, v1
	v_ashrrev_i32_e32 v7, 31, v6
	v_lshl_add_u64 v[30:31], s[96:97], 0, v[28:29]
	s_add_i32 s19, s18, s36
	v_lshlrev_b64 v[6:7], 7, v[6:7]
	s_lshl_b32 s45, s19, 1
	v_lshl_add_u64 v[8:9], v[30:31], 0, v[6:7]
	s_add_u32 s96, s85, s45
	global_load_dwordx4 v[12:15], v[8:9], off
	v_add_co_u32_e32 v8, vcc, s87, v8
	s_addc_u32 s97, s98, 0
	v_ashrrev_i32_e32 v5, 31, v4
	v_addc_co_u32_e32 v9, vcc, 0, v9, vcc
	v_lshl_add_u64 v[24:25], s[96:97], 0, v[28:29]
	v_lshlrev_b64 v[6:7], 12, v[4:5]
	global_load_dwordx4 v[20:23], v[8:9], off
	v_add_u32_e32 v8, 32, v4
	v_lshl_add_u64 v[16:17], v[24:25], 0, v[6:7]
	v_ashrrev_i32_e32 v9, 31, v8
	global_load_dwordx4 v[16:19], v[16:17], off offset:-256
	v_lshlrev_b64 v[32:33], 12, v[8:9]
	v_lshl_add_u64 v[24:25], v[24:25], 0, v[32:33]
	global_load_dwordx4 v[24:27], v[24:25], off offset:-256
	v_mad_u64_u32 v[118:119], s[96:97], v4, s13, v[28:29]
	s_barrier
; template <int MODE>
; DI void attn_item(const Params& p, int layer, int b, int hq, int qb, u16* lds, const int WAVE_S) {
;     ...
;   float m_run, l_run;
;   float slope2 = 0.f;
;   if (MODE == 0) { m_run = 0.f; l_run = 0.f; }
;   else {
;     m_run = p.sink[layer * 8 + hq] * LOG2E;
;     l_run = (h == 0) ? 1.f : 0.f;
;     slope2 = exp2f(-(float)(hq + 1)) * LOG2E;
;   }
;   f32x16 negm;
; #pragma unroll
;   for (int i = 0; i < 16; ++i) negm[i] = -m_run;
;   f32x16 o[2];
; #pragma unroll
;   for (int dt = 0; dt < 2; ++dt)
; #pragma unroll
;     for (int i = 0; i < 16; ++i) o[dt][i] = 0.f;
;   const int lr = tid >> 3, lc = (tid & 7) * 8;
;   u32x4 kr[2], vr[2];
;   {
;     const int kb = kbase0 + t_begin * 64;
; #pragma unroll
;     for (int it = 0; it < 2; ++it) {
;       kr[it] = *(const u32x4*)(kp + (size_t)(kb + lr + 32 * it) * 64 + lc);
;       vr[it] = *(const u32x4*)(vp + (size_t)(lr + 32 * it) * SEQ + kb + lc);
;     }
;   }
;   __syncthreads();
;   {
;     u16* K0 = lds + (t_begin & 1) * 128 * LSTR;
; #pragma unroll
;     for (int it = 0; it < 2; ++it) {
;       *(u32x4*)(K0 + (lr + 32 * it) * LSTR + lc) = kr[it];
;       *(u32x4*)(K0 + 64 * LSTR + (lr + 32 * it) * LSTR + lc) = vr[it];
;     }
;     if (t_begin + 1 < t_end) {
;       const int kb = kbase0 + (t_begin + 1) * 64;
; #pragma unroll
;       for (int it = 0; it < 2; ++it) {
;         kr[it] = *(const u32x4*)(kp + (size_t)(kb + lr + 32 * it) * 64 + lc);
;         vr[it] = *(const u32x4*)(vp + (size_t)(lr + 32 * it) * SEQ + kb + lc);
;       }
;     }
;   }
	s_ashr_i32 s35, s34, 31
	s_lshl_b64 s[96:97], s[34:35], 1
	s_waitcnt vmcnt(3)
	ds_write_b128 v118, v[12:15]
	s_waitcnt vmcnt(1)
	ds_write_b128 v118, v[16:19] offset:9216
	ds_write_b128 v118, v[20:23] offset:4608
	s_waitcnt vmcnt(0)
	ds_write_b128 v118, v[24:27] offset:13824
	v_add3_u32 v12, s34, 64, v4
	v_ashrrev_i32_e32 v13, 31, v12
	v_lshlrev_b64 v[12:13], 7, v[12:13]
	s_add_u32 s96, s85, s96
	v_lshl_add_u64 v[12:13], v[30:31], 0, v[12:13]
	s_addc_u32 s97, s98, s97
	global_load_dwordx4 v[98:101], v[12:13], off
	v_add_co_u32_e32 v12, vcc, s87, v12
	v_lshl_add_u64 v[14:15], s[96:97], 0, v[28:29]
	s_nop 0
	v_addc_co_u32_e32 v13, vcc, 0, v13, vcc
	v_lshl_add_u64 v[16:17], v[14:15], 0, v[6:7]
	global_load_dwordx4 v[106:109], v[12:13], off
	v_lshl_add_u64 v[12:13], v[14:15], 0, v[32:33]
	global_load_dwordx4 v[102:105], v[16:17], off offset:128
	global_load_dwordx4 v[110:113], v[12:13], off offset:128
	s_add_i32 s35, s17, s44
	s_lshl_b32 s35, s35, 18
	s_and_b32 s35, s35, 0x1f80000
	v_readlane_b32 s52, v166, 22
	v_readlane_b32 s53, v166, 23
	s_add_u32 s44, s52, s45
	s_addc_u32 s45, s53, 0
	s_add_u32 s44, s44, s35
	s_addc_u32 s45, s45, 0
	v_lshl_add_u64 v[122:123], s[44:45], 0, v[6:7]
	v_readlane_b32 s44, v166, 20
	s_add_u32 s44, s44, s35
	v_readlane_b32 s35, v166, 21
	v_add_u32_e32 v6, s19, v8
	s_addc_u32 s45, s35, 0
	v_add_u32_e32 v4, s19, v4
	s_add_i32 s85, s19, 0xffffffbf
	s_sub_i32 s96, 0x41, s19
	s_movk_i32 s19, 0xffe0
	v_lshlrev_b32_e32 v119, 2, v11
	v_mad_u32_u24 v131, v114, s13, v0
	v_and_b32_e32 v0, 7, v3
	v_bfi_b32 v3, s19, v10, v3
	s_mov_b64 s[54:55], s[62:63]
	s_mov_b64 s[58:59], s[66:67]
	v_mul_f32_e32 v115, 0x3fb8aa3b, v2
	v_ashrrev_i32_e32 v7, 31, v6
	v_ashrrev_i32_e32 v5, 31, v4
	v_sub_u32_e32 v3, v3, v119
	v_mov_b32_e32 v32, v1
	v_mov_b32_e32 v33, v1
	v_readlane_b32 s58, v166, 54
	v_readlane_b32 s54, v166, 50
	v_readlane_b32 s66, v166, 48
	v_readlane_b32 s56, v166, 52
	v_xor_b32_e32 v2, 0x80000000, v115
	v_mul_f32_e32 v120, 0x3fb8aa3b, v34
	s_mov_b32 s52, 0xc1800000
	v_lshlrev_b64 v[6:7], 7, v[6:7]
	v_lshlrev_b64 v[4:5], 7, v[4:5]
	v_subrev_u32_e32 v3, s18, v3
	v_mov_b32_e32 v18, v1
	v_mov_b32_e32 v19, v1
	v_mov_b32_e32 v20, v1
	v_mov_b32_e32 v21, v1
	v_mov_b32_e32 v22, v1
	v_mov_b32_e32 v23, v1
	v_mov_b32_e32 v24, v1
	v_mov_b32_e32 v25, v1
	v_mov_b32_e32 v26, v1
	v_mov_b32_e32 v27, v1
	v_mov_b32_e32 v28, v1
	v_mov_b32_e32 v30, v1
	v_mov_b32_e32 v31, v1
	v_mov_b64_e32 v[48:49], v[32:33]
	v_readlane_b32 s59, v166, 55
	v_readlane_b32 s55, v166, 51
	v_readlane_b32 s67, v166, 49
	v_readlane_b32 s65, v166, 47
	v_readlane_b32 s64, v166, 42
	v_readlane_b32 s57, v166, 53
	v_or_b32_e32 v130, 31, v116
	v_mov_b32_e32 v121, v120
	v_lshlrev_b32_e32 v0, 4, v0
	s_mov_b32 s53, 0xc1880000
	v_lshl_add_u64 v[124:125], s[44:45], 0, v[6:7]
	v_lshl_add_u64 v[126:127], s[44:45], 0, v[4:5]
	s_add_i32 s35, s28, 2
	v_add_u32_e32 v132, 0x80, v3
	s_lshl_b32 s97, s28, 7
	v_mov_b64_e32 v[46:47], v[30:31]
	v_mov_b64_e32 v[44:45], v[28:29]
	v_mov_b64_e32 v[42:43], v[26:27]
	v_mov_b64_e32 v[40:41], v[24:25]
	v_mov_b64_e32 v[38:39], v[22:23]
	v_mov_b64_e32 v[36:37], v[20:21]
	v_mov_b64_e32 v[34:35], v[18:19]
	v_mov_b32_e32 v3, v2
	v_mov_b32_e32 v4, v2
	v_mov_b32_e32 v5, v2
	v_mov_b32_e32 v6, v2
	v_mov_b32_e32 v7, v2
	v_mov_b32_e32 v8, v2
	v_mov_b32_e32 v9, v2
	v_mov_b32_e32 v10, v2
	v_mov_b32_e32 v11, v2
	v_mov_b32_e32 v12, v2
	v_mov_b32_e32 v13, v2
	v_mov_b32_e32 v14, v2
	v_mov_b32_e32 v15, v2
	v_mov_b32_e32 v16, v2
	v_mov_b32_e32 v17, v2
	v_mov_b32_e32 v134, v132
	v_mov_b32_e32 v135, v132
	s_nop 1
	v_min_i32_dpp v134, v134, v134 quad_perm:[1,0,3,2] row_mask:0xf bank_mask:0xf
	v_max_i32_dpp v135, v135, v135 quad_perm:[1,0,3,2] row_mask:0xf bank_mask:0xf
	s_nop 1
	v_min_i32_dpp v134, v134, v134 quad_perm:[2,3,0,1] row_mask:0xf bank_mask:0xf
	v_max_i32_dpp v135, v135, v135 quad_perm:[2,3,0,1] row_mask:0xf bank_mask:0xf
	s_nop 1
	v_min_i32_dpp v134, v134, v134 row_half_mirror row_mask:0xf bank_mask:0xf
	v_max_i32_dpp v135, v135, v135 row_half_mirror row_mask:0xf bank_mask:0xf
	s_nop 1
	v_min_i32_dpp v134, v134, v134 row_mirror row_mask:0xf bank_mask:0xf
	v_max_i32_dpp v135, v135, v135 row_mirror row_mask:0xf bank_mask:0xf
	s_nop 1
	v_readlane_b32 s100, v134, 0
	v_readlane_b32 s18, v134, 16
	v_readlane_b32 s19, v134, 32
	v_readlane_b32 s32, v134, 48
	s_min_i32 s100, s100, s18
	s_min_i32 s19, s19, s32
	s_min_i32 s100, s100, s19
	v_readlane_b32 s101, v135, 0
	v_readlane_b32 s18, v135, 16
	v_readlane_b32 s19, v135, 32
	v_readlane_b32 s32, v135, 48
	s_max_i32 s101, s101, s18
	s_max_i32 s19, s19, s32
	s_max_i32 s101, s101, s19
	s_branch .LBB0_181

; template <int MODE>
; DI void attn_item(const Params& p, int layer, int b, int hq, int qb, u16* lds, const int WAVE_S) {
;     ...
;   for (int t = t_begin; t < t_end; ++t) {
;     __syncthreads();
;     const u16* Ks = lds + (t & 1) * 128 * LSTR;
;     const u16* Vs = Ks + 64 * LSTR;
;     if (t + 1 < t_end) {
.LBB0_180:
	s_or_b64 exec, exec, s[44:45]
	s_mov_b64 s[18:19], 0x80
	s_add_i32 s35, s35, 1
	s_add_i32 s85, s85, 64
	s_sub_i32 s96, s96, 64
	s_add_i32 s34, s34, 64
	s_addk_i32 s97, 0x80
	s_add_i32 s28, s28, 1
	v_lshl_add_u64 v[122:123], v[122:123], 0, s[18:19]
	v_lshl_add_u64 v[124:125], v[124:125], 0, s[24:25]
	v_lshl_add_u64 v[126:127], v[126:127], 0, s[24:25]
	s_sub_i32 s100, s100, 64
	s_sub_i32 s101, s101, 64
	s_cmp_lt_u32 s98, s51
	v_subrev_u32_e32 v132, 64, v132
	s_cbranch_scc0 .LBB0_189

; #define MFMA32(a, b, c) __builtin_amdgcn_mfma_f32_32x32x16_bf16((a), (b), (c), 0, 0, 0)
; template <int MODE>
; DI void attn_item(const Params& p, int layer, int b, int hq, int qb, u16* lds, const int WAVE_S) {
;     ...
;     bool live = true;
;     if (MODE == 1) {
;       const int kb = kbase0 + t * 64;
;       const int gap = (kb > q0 + 31) ? kb - (q0 + 31) : ((kb + 63 < q0) ? q0 - (kb + 63) : 0);
;       live = gap <= 128;
;     }
;     if (live) {
;     f32x16 sc[2];
; #pragma unroll
;     for (int k2 = 0; k2 < 2; ++k2) {
; #pragma unroll
;       for (int ks = 0; ks < 4; ++ks) {
;         const bf16x8 kf = *(const bf16x8*)(Ks + (k2 * 32 + r) * LSTR + ks * 16 + h * 8);
;         sc[k2] = (ks == 0) ? MFMA32(kf, qf[0], negm) : MFMA32(kf, qf[ks], sc[k2]);
;       }
;     }
;     if (MODE == 1) {
;       const float tposf = (float)(q0 + r - (kbase0 + t * 64) - 4 * h);
; #pragma unroll
;       for (int k2 = 0; k2 < 2; ++k2)
; #pragma unroll
;         for (int i = 0; i < 16; ++i) {
;           const float dist = fabsf(tposf - (float)(k2 * 32 + (i & 3) + 8 * (i >> 2)));
;           sc[k2][i] = (dist <= 128.f) ? (sc[k2][i] - slope2 * dist) : -1e30f;
;         }
;     }
;     float mx0 = fmaxf(fmaxf(sc[0][0], sc[0][1]), sc[0][2]), mx1 = fmaxf(fmaxf(sc[1][0], sc[1][1]), sc[1][2]);
; #pragma unroll
;     for (int i = 3; i < 15; i += 2) { mx0 = fmaxf(fmaxf(mx0, sc[0][i]), sc[0][i + 1]); mx1 = fmaxf(fmaxf(mx1, sc[1][i]), sc[1][i + 1]); }
;     float mx = fmaxf(fmaxf(mx0, mx1), fmaxf(sc[0][15], sc[1][15]));
.LBB0_184:
	v_max_i32_e32 v50, s85, v116
	v_add_u32_e32 v50, s96, v50
	v_cmp_gt_i32_e32 vcc, s34, v130
	s_and_saveexec_b64 s[18:19], vcc
	s_lshl_b32 s44, s28, 6
	s_add_i32 s44, s44, s84
	v_sub_u32_e32 v50, s44, v130
	s_or_b64 exec, exec, s[18:19]
	s_movk_i32 s18, 0x81
	v_cmp_gt_i32_e32 vcc, s18, v50
	s_and_saveexec_b64 s[44:45], vcc
	s_cbranch_execz .LBB0_180
	s_and_b32 s18, s97, 0x80
	s_mulk_i32 s18, 0x90
	v_add_u32_e32 v133, s18, v131
	ds_read_b128 v[50:53], v133
	ds_read_b128 v[54:57], v133 offset:32
	ds_read_b128 v[134:137], v133 offset:4608
	v_cvt_f32_i32_e32 v128, v132
	s_waitcnt lgkmcnt(2)
	v_mfma_f32_32x32x16_bf16 v[66:81], v[50:53], v[82:85], v[2:17]
	ds_read_b128 v[50:53], v133 offset:64
	s_waitcnt lgkmcnt(2)
	v_mfma_f32_32x32x16_bf16 v[66:81], v[54:57], v[86:89], v[66:81]
	s_waitcnt lgkmcnt(0)
	v_mfma_f32_32x32x16_bf16 v[66:81], v[50:53], v[90:93], v[66:81]
	ds_read_b128 v[50:53], v133 offset:96
	s_waitcnt lgkmcnt(0)
	v_mfma_f32_32x32x16_bf16 v[66:81], v[50:53], v[94:97], v[66:81]
	v_mov_b64_e32 v[64:65], v[16:17]
	v_mov_b64_e32 v[62:63], v[14:15]
	v_mov_b64_e32 v[60:61], v[12:13]
	v_mov_b64_e32 v[58:59], v[10:11]
	v_mov_b64_e32 v[56:57], v[8:9]
	v_mov_b64_e32 v[54:55], v[6:7]
	v_mov_b64_e32 v[52:53], v[4:5]
	v_mov_b64_e32 v[50:51], v[2:3]
	s_nop 1
	v_mfma_f32_32x32x16_bf16 v[50:65], v[134:137], v[82:85], v[50:65]
	ds_read_b128 v[134:137], v133 offset:4640
	s_waitcnt lgkmcnt(0)
	v_mfma_f32_32x32x16_bf16 v[50:65], v[134:137], v[86:89], v[50:65]
	ds_read_b128 v[134:137], v133 offset:4672
	s_waitcnt lgkmcnt(0)
	v_mfma_f32_32x32x16_bf16 v[50:65], v[134:137], v[90:93], v[50:65]
	ds_read_b128 v[134:137], v133 offset:4704
	s_waitcnt lgkmcnt(0)
	v_mfma_f32_32x32x16_bf16 v[50:65], v[134:137], v[94:97], v[50:65]
	s_cmp_gt_i32 s101, 0x80
	s_cbranch_scc1 .Lwin_masked
	s_cmp_lt_i32 s100, 0xffffffbb
	s_cbranch_scc1 .Lwin_masked
	v_add_f32_e32 v136, -1.0, v128
	v_fma_f32 v134, -v120, |v128|, v66
	v_fma_f32 v135, -v121, |v136|, v67
	v_mov_b32_e32 v66, v135
	v_mov_b32_e32 v67, v134
	v_pk_add_f32 v[134:135], v[128:129], s[2:3] op_sel_hi:[0,1]
	v_fma_f32 v136, -v120, |v134|, v68
	v_fma_f32 v137, -v121, |v135|, v69
	v_mov_b32_e32 v68, v137
	v_pk_add_f32 v[134:135], v[128:129], s[38:39] op_sel_hi:[0,1]
	v_mov_b32_e32 v69, v136
	v_fma_f32 v136, -v120, |v134|, v70
	v_fma_f32 v137, -v121, |v135|, v71
	v_mov_b32_e32 v70, v137
	v_pk_add_f32 v[134:135], v[128:129], s[4:5] op_sel_hi:[0,1]
	v_mov_b32_e32 v71, v136
	v_fma_f32 v136, -v120, |v134|, v72
	v_fma_f32 v137, -v121, |v135|, v73
	v_mov_b32_e32 v72, v137
	v_pk_add_f32 v[134:135], v[128:129], s[52:53] op_sel_hi:[0,1]
	v_mov_b32_e32 v73, v136
	v_fma_f32 v136, -v120, |v134|, v74
	v_fma_f32 v137, -v121, |v135|, v75
	v_mov_b32_e32 v74, v137
	v_pk_add_f32 v[134:135], v[128:129], s[26:27] op_sel_hi:[0,1]
	v_mov_b32_e32 v75, v136
	v_fma_f32 v136, -v120, |v134|, v76
	v_fma_f32 v137, -v121, |v135|, v77
	v_mov_b32_e32 v76, v137
	v_pk_add_f32 v[134:135], v[128:129], s[76:77] op_sel_hi:[0,1]
	v_mov_b32_e32 v77, v136
	v_fma_f32 v136, -v120, |v134|, v78
	v_fma_f32 v137, -v121, |v135|, v79
	v_mov_b32_e32 v78, v137
	v_pk_add_f32 v[134:135], v[128:129], s[22:23] op_sel_hi:[0,1]
	v_mov_b32_e32 v79, v136
	v_fma_f32 v136, -v120, |v134|, v80
	v_fma_f32 v137, -v121, |v135|, v81
	v_mov_b32_e32 v80, v137
	v_pk_add_f32 v[134:135], v[128:129], s[10:11] op_sel_hi:[0,1]
	v_mov_b32_e32 v81, v136
	v_fma_f32 v136, -v120, |v134|, v50
	v_fma_f32 v137, -v121, |v135|, v51
	v_mov_b32_e32 v50, v137
	v_pk_add_f32 v[134:135], v[128:129], s[30:31] op_sel_hi:[0,1]
	v_mov_b32_e32 v51, v136
	v_fma_f32 v136, -v120, |v134|, v52
	v_fma_f32 v137, -v121, |v135|, v53
	v_mov_b32_e32 v52, v137
	v_pk_add_f32 v[134:135], v[128:129], s[20:21] op_sel_hi:[0,1]
	v_mov_b32_e32 v53, v136
	v_fma_f32 v136, -v120, |v134|, v54
	v_fma_f32 v137, -v121, |v135|, v55
	v_mov_b32_e32 v54, v137
	v_pk_add_f32 v[134:135], v[128:129], s[6:7] op_sel_hi:[0,1]
	v_mov_b32_e32 v55, v136
	v_fma_f32 v136, -v120, |v134|, v56
	v_fma_f32 v137, -v121, |v135|, v57
	v_mov_b32_e32 v56, v137
	v_pk_add_f32 v[134:135], v[128:129], s[42:43] op_sel_hi:[0,1]
	v_mov_b32_e32 v57, v136
	v_fma_f32 v136, -v120, |v134|, v58
	v_fma_f32 v137, -v121, |v135|, v59
	v_mov_b32_e32 v58, v137
	v_pk_add_f32 v[134:135], v[128:129], s[14:15] op_sel_hi:[0,1]
	v_mov_b32_e32 v59, v136
	v_fma_f32 v136, -v120, |v134|, v60
	v_fma_f32 v137, -v121, |v135|, v61
	v_mov_b32_e32 v60, v137
	v_pk_add_f32 v[134:135], v[128:129], s[82:83] op_sel_hi:[0,1]
	v_mov_b32_e32 v61, v136
	v_fma_f32 v136, -v120, |v134|, v62
	v_fma_f32 v137, -v121, |v135|, v63
	v_mov_b32_e32 v62, v137
	v_pk_add_f32 v[134:135], v[128:129], s[8:9] op_sel_hi:[0,1]
	v_mov_b32_e32 v63, v136
	v_fma_f32 v136, -v120, |v134|, v64
	v_fma_f32 v137, -v121, |v135|, v65
	v_max3_f32 v128, v67, v66, v69
	v_max3_f32 v128, v128, v68, v71
	v_mov_b32_e32 v64, v137
	v_max3_f32 v134, v51, v50, v53
	v_max3_f32 v134, v134, v52, v55
	v_max3_f32 v128, v128, v70, v73
	v_max3_f32 v134, v134, v54, v57
	v_max3_f32 v128, v128, v72, v75
	v_max3_f32 v134, v134, v56, v59
	v_max3_f32 v128, v128, v74, v77
	v_max3_f32 v134, v134, v58, v61
	v_mov_b32_e32 v65, v136
	v_max3_f32 v128, v128, v76, v79
	v_max3_f32 v134, v134, v60, v63
	v_max3_f32 v128, v128, v78, v81
	v_max3_f32 v134, v134, v62, v65
	v_max_f32_e32 v135, v80, v64
	v_max3_f32 v128, v128, v134, v135
	v_mov_b32_e32 v134, v128
	s_nop 1
	v_permlane32_swap_b32_e32 v128, v134
	v_max_f32_e32 v134, v134, v134
	v_max_f32_e32 v128, v128, v128
	v_max_f32_e32 v128, v128, v134
	s_branch .Lwin_join
; template <int MODE>
; DI void attn_item(const Params& p, int layer, int b, int hq, int qb, u16* lds, const int WAVE_S) {
;     ...
;     if (MODE == 1) {
;       const float tposf = (float)(q0 + r - (kbase0 + t * 64) - 4 * h);
; #pragma unroll
;       for (int k2 = 0; k2 < 2; ++k2)
; #pragma unroll
;         for (int i = 0; i < 16; ++i) {
;           const float dist = fabsf(tposf - (float)(k2 * 32 + (i & 3) + 8 * (i >> 2)));
;           sc[k2][i] = (dist <= 128.f) ? (sc[k2][i] - slope2 * dist) : -1e30f;
;         }
;     }
;     float mx0 = fmaxf(fmaxf(sc[0][0], sc[0][1]), sc[0][2]), mx1 = fmaxf(fmaxf(sc[1][0], sc[1][1]), sc[1][2]);
; #pragma unroll
;     for (int i = 3; i < 15; i += 2) { mx0 = fmaxf(fmaxf(mx0, sc[0][i]), sc[0][i + 1]); mx1 = fmaxf(fmaxf(mx1, sc[1][i]), sc[1][i + 1]); }
;     float mx = fmaxf(fmaxf(mx0, mx1), fmaxf(sc[0][15], sc[1][15]));
.Lwin_masked:
	v_add_f32_e32 v136, -1.0, v128
	s_nop 0
	s_nop 0
	v_fma_f32 v134, -v120, |v128|, v66
	v_fma_f32 v135, -v121, |v136|, v67
	v_cmp_le_f32_e64 vcc, |v136|, s89
	s_nop 1
	v_cndmask_b32_e32 v66, v146, v135, vcc
	v_cmp_le_f32_e64 vcc, |v128|, s89
	s_nop 1
	v_cndmask_b32_e32 v67, v146, v134, vcc
	v_pk_add_f32 v[134:135], v[128:129], s[2:3] op_sel_hi:[0,1]
	s_nop 0
	s_nop 0
	v_fma_f32 v136, -v120, |v134|, v68
	v_fma_f32 v137, -v121, |v135|, v69
	v_cmp_le_f32_e64 vcc, |v135|, s89
	s_nop 1
	v_cndmask_b32_e32 v68, v146, v137, vcc
	v_cmp_le_f32_e64 vcc, |v134|, s89
	v_pk_add_f32 v[134:135], v[128:129], s[38:39] op_sel_hi:[0,1]
	s_nop 0
	v_cndmask_b32_e32 v69, v146, v136, vcc
	s_nop 0
	v_fma_f32 v136, -v120, |v134|, v70
	v_fma_f32 v137, -v121, |v135|, v71
	v_cmp_le_f32_e64 vcc, |v135|, s89
	s_nop 1
	v_cndmask_b32_e32 v70, v146, v137, vcc
	v_cmp_le_f32_e64 vcc, |v134|, s89
	v_pk_add_f32 v[134:135], v[128:129], s[4:5] op_sel_hi:[0,1]
	s_nop 0
	v_cndmask_b32_e32 v71, v146, v136, vcc
	s_nop 0
	v_fma_f32 v136, -v120, |v134|, v72
	v_fma_f32 v137, -v121, |v135|, v73
	v_cmp_le_f32_e64 vcc, |v135|, s89
	s_nop 1
	v_cndmask_b32_e32 v72, v146, v137, vcc
	v_cmp_le_f32_e64 vcc, |v134|, s89
	v_pk_add_f32 v[134:135], v[128:129], s[52:53] op_sel_hi:[0,1]
	s_nop 0
	v_cndmask_b32_e32 v73, v146, v136, vcc
	s_nop 0
	v_fma_f32 v136, -v120, |v134|, v74
	v_fma_f32 v137, -v121, |v135|, v75
	v_cmp_le_f32_e64 vcc, |v135|, s89
	s_nop 1
	v_cndmask_b32_e32 v74, v146, v137, vcc
	v_cmp_le_f32_e64 vcc, |v134|, s89
	v_pk_add_f32 v[134:135], v[128:129], s[26:27] op_sel_hi:[0,1]
	s_nop 0
	v_cndmask_b32_e32 v75, v146, v136, vcc
	s_nop 0
	v_fma_f32 v136, -v120, |v134|, v76
	v_fma_f32 v137, -v121, |v135|, v77
	v_cmp_le_f32_e64 vcc, |v135|, s89
	s_nop 1
	v_cndmask_b32_e32 v76, v146, v137, vcc
	v_cmp_le_f32_e64 vcc, |v134|, s89
	v_pk_add_f32 v[134:135], v[128:129], s[76:77] op_sel_hi:[0,1]
	s_nop 0
	v_cndmask_b32_e32 v77, v146, v136, vcc
	s_nop 0
	v_fma_f32 v136, -v120, |v134|, v78
	v_fma_f32 v137, -v121, |v135|, v79
	v_cmp_le_f32_e64 vcc, |v135|, s89
	s_nop 1
	v_cndmask_b32_e32 v78, v146, v137, vcc
	v_cmp_le_f32_e64 vcc, |v134|, s89
	v_pk_add_f32 v[134:135], v[128:129], s[22:23] op_sel_hi:[0,1]
	s_nop 0
	v_cndmask_b32_e32 v79, v146, v136, vcc
	s_nop 0
	v_fma_f32 v136, -v120, |v134|, v80
	v_fma_f32 v137, -v121, |v135|, v81
	v_cmp_le_f32_e64 vcc, |v135|, s89
	s_nop 1
	v_cndmask_b32_e32 v80, v146, v137, vcc
	v_cmp_le_f32_e64 vcc, |v134|, s89
	v_pk_add_f32 v[134:135], v[128:129], s[10:11] op_sel_hi:[0,1]
	s_nop 0
	v_cndmask_b32_e32 v81, v146, v136, vcc
	s_nop 0
	v_fma_f32 v136, -v120, |v134|, v50
	v_fma_f32 v137, -v121, |v135|, v51
	v_cmp_le_f32_e64 vcc, |v135|, s89
	s_nop 1
	v_cndmask_b32_e32 v50, v146, v137, vcc
	v_cmp_le_f32_e64 vcc, |v134|, s89
	v_pk_add_f32 v[134:135], v[128:129], s[30:31] op_sel_hi:[0,1]
	s_nop 0
	v_cndmask_b32_e32 v51, v146, v136, vcc
	s_nop 0
	v_fma_f32 v136, -v120, |v134|, v52
	v_fma_f32 v137, -v121, |v135|, v53
	v_cmp_le_f32_e64 vcc, |v135|, s89
	s_nop 1
	v_cndmask_b32_e32 v52, v146, v137, vcc
	v_cmp_le_f32_e64 vcc, |v134|, s89
	v_pk_add_f32 v[134:135], v[128:129], s[20:21] op_sel_hi:[0,1]
	s_nop 0
	v_cndmask_b32_e32 v53, v146, v136, vcc
	s_nop 0
	v_fma_f32 v136, -v120, |v134|, v54
	v_fma_f32 v137, -v121, |v135|, v55
	v_cmp_le_f32_e64 vcc, |v135|, s89
	s_nop 1
	v_cndmask_b32_e32 v54, v146, v137, vcc
	v_cmp_le_f32_e64 vcc, |v134|, s89
	v_pk_add_f32 v[134:135], v[128:129], s[6:7] op_sel_hi:[0,1]
	s_nop 0
	v_cndmask_b32_e32 v55, v146, v136, vcc
	s_nop 0
	v_fma_f32 v136, -v120, |v134|, v56
	v_fma_f32 v137, -v121, |v135|, v57
	v_cmp_le_f32_e64 vcc, |v135|, s89
	s_nop 1
	v_cndmask_b32_e32 v56, v146, v137, vcc
	v_cmp_le_f32_e64 vcc, |v134|, s89
	v_pk_add_f32 v[134:135], v[128:129], s[42:43] op_sel_hi:[0,1]
	s_nop 0
	v_cndmask_b32_e32 v57, v146, v136, vcc
	s_nop 0
	v_fma_f32 v136, -v120, |v134|, v58
	v_fma_f32 v137, -v121, |v135|, v59
	v_cmp_le_f32_e64 vcc, |v135|, s89
	s_nop 1
	v_cndmask_b32_e32 v58, v146, v137, vcc
	v_cmp_le_f32_e64 vcc, |v134|, s89
	v_pk_add_f32 v[134:135], v[128:129], s[14:15] op_sel_hi:[0,1]
	s_nop 0
	v_cndmask_b32_e32 v59, v146, v136, vcc
	s_nop 0
	v_fma_f32 v136, -v120, |v134|, v60
	v_fma_f32 v137, -v121, |v135|, v61
	v_cmp_le_f32_e64 vcc, |v135|, s89
	s_nop 1
	v_cndmask_b32_e32 v60, v146, v137, vcc
	v_cmp_le_f32_e64 vcc, |v134|, s89
	v_pk_add_f32 v[134:135], v[128:129], s[82:83] op_sel_hi:[0,1]
	s_nop 0
	v_cndmask_b32_e32 v61, v146, v136, vcc
	s_nop 0
	v_fma_f32 v136, -v120, |v134|, v62
	v_fma_f32 v137, -v121, |v135|, v63
	v_cmp_le_f32_e64 vcc, |v135|, s89
	s_nop 1
	v_cndmask_b32_e32 v62, v146, v137, vcc
	v_cmp_le_f32_e64 vcc, |v134|, s89
	v_pk_add_f32 v[134:135], v[128:129], s[8:9] op_sel_hi:[0,1]
	s_nop 0
	v_cndmask_b32_e32 v63, v146, v136, vcc
	s_nop 0
	v_fma_f32 v136, -v120, |v134|, v64
	v_fma_f32 v137, -v121, |v135|, v65
	v_cmp_le_f32_e64 vcc, |v135|, s89
	v_max3_f32 v128, v67, v66, v69
	v_max3_f32 v128, v128, v68, v71
	v_cndmask_b32_e32 v64, v146, v137, vcc
	v_cmp_le_f32_e64 vcc, |v134|, s89
	v_max3_f32 v134, v51, v50, v53
	v_max3_f32 v134, v134, v52, v55
	v_max3_f32 v128, v128, v70, v73
	v_max3_f32 v134, v134, v54, v57
	v_max3_f32 v128, v128, v72, v75
	v_max3_f32 v134, v134, v56, v59
	v_max3_f32 v128, v128, v74, v77
	v_max3_f32 v134, v134, v58, v61
	v_cndmask_b32_e32 v65, v146, v136, vcc
	v_max3_f32 v128, v128, v76, v79
	v_max3_f32 v134, v134, v60, v63
	v_max3_f32 v128, v128, v78, v81
	v_max3_f32 v134, v134, v62, v65
	v_max_f32_e32 v135, v80, v64
	v_max3_f32 v128, v128, v134, v135
	v_mov_b32_e32 v134, v128
	s_nop 1
	v_permlane32_swap_b32_e32 v128, v134
	v_max_f32_e32 v134, v134, v134
	v_max_f32_e32 v128, v128, v128
	v_max_f32_e32 v128, v128, v134
; template <int MODE>
; DI void attn_item(const Params& p, int layer, int b, int hq, int qb, u16* lds, const int WAVE_S) {
;     ...
;     if (__any(mx > 8.0f)) {
;       const float delta = fmaxf(mx, 0.f);
;       const float al = __builtin_amdgcn_exp2f(-delta);
; #pragma unroll
;       for (int k2 = 0; k2 < 2; ++k2)
; #pragma unroll
;         for (int i = 0; i < 16; ++i) sc[k2][i] -= delta;
; #pragma unroll
;       for (int dt = 0; dt < 2; ++dt)
; #pragma unroll
;         for (int i = 0; i < 16; ++i) o[dt][i] *= al;
;       l_run *= al;
;       m_run += delta;
; #pragma unroll
;       for (int i = 0; i < 16; ++i) negm[i] = -m_run;
;     }
.Lwin_join:
	v_cmp_lt_f32_e32 vcc, s90, v128
	s_cbranch_vccz .LBB0_179
	v_max_f32_e32 v2, v128, v128
	v_max_f32_e32 v2, 0, v2
	v_exp_f32_e64 v4, -v2
	v_add_f32_e32 v115, v115, v2
	v_sub_f32_e32 v67, v67, v2
	v_sub_f32_e32 v66, v66, v2
	v_sub_f32_e32 v69, v69, v2
	v_sub_f32_e32 v68, v68, v2
	v_sub_f32_e32 v71, v71, v2
	v_sub_f32_e32 v70, v70, v2
	v_sub_f32_e32 v73, v73, v2
	v_sub_f32_e32 v72, v72, v2
	v_sub_f32_e32 v75, v75, v2
	v_sub_f32_e32 v74, v74, v2
	v_sub_f32_e32 v77, v77, v2
	v_sub_f32_e32 v76, v76, v2
	v_sub_f32_e32 v79, v79, v2
	v_sub_f32_e32 v78, v78, v2
	v_sub_f32_e32 v81, v81, v2
	v_sub_f32_e32 v80, v80, v2
	v_sub_f32_e32 v51, v51, v2
	v_sub_f32_e32 v50, v50, v2
	v_sub_f32_e32 v53, v53, v2
	v_sub_f32_e32 v52, v52, v2
	v_sub_f32_e32 v55, v55, v2
	v_sub_f32_e32 v54, v54, v2
	v_sub_f32_e32 v57, v57, v2
	v_sub_f32_e32 v56, v56, v2
	v_sub_f32_e32 v59, v59, v2
	v_sub_f32_e32 v58, v58, v2
	v_sub_f32_e32 v61, v61, v2
	v_sub_f32_e32 v60, v60, v2
	v_sub_f32_e32 v63, v63, v2
	v_sub_f32_e32 v62, v62, v2
	v_sub_f32_e32 v65, v65, v2
	v_sub_f32_e32 v64, v64, v2
	v_xor_b32_e32 v2, 0x80000000, v115
	v_pk_mul_f32 v[32:33], v[32:33], v[4:5] op_sel_hi:[1,0]
	v_pk_mul_f32 v[30:31], v[30:31], v[4:5] op_sel_hi:[1,0]
	v_pk_mul_f32 v[28:29], v[28:29], v[4:5] op_sel_hi:[1,0]
	v_pk_mul_f32 v[26:27], v[26:27], v[4:5] op_sel_hi:[1,0]
	v_pk_mul_f32 v[24:25], v[24:25], v[4:5] op_sel_hi:[1,0]
	v_pk_mul_f32 v[22:23], v[22:23], v[4:5] op_sel_hi:[1,0]
	v_pk_mul_f32 v[20:21], v[20:21], v[4:5] op_sel_hi:[1,0]
	v_pk_mul_f32 v[18:19], v[18:19], v[4:5] op_sel_hi:[1,0]
	v_pk_mul_f32 v[48:49], v[48:49], v[4:5] op_sel_hi:[1,0]
	v_pk_mul_f32 v[46:47], v[46:47], v[4:5] op_sel_hi:[1,0]
	v_pk_mul_f32 v[44:45], v[44:45], v[4:5] op_sel_hi:[1,0]
	v_pk_mul_f32 v[42:43], v[42:43], v[4:5] op_sel_hi:[1,0]
	v_pk_mul_f32 v[40:41], v[40:41], v[4:5] op_sel_hi:[1,0]
	v_pk_mul_f32 v[38:39], v[38:39], v[4:5] op_sel_hi:[1,0]
	v_pk_mul_f32 v[36:37], v[36:37], v[4:5] op_sel_hi:[1,0]
	v_pk_mul_f32 v[34:35], v[34:35], v[4:5] op_sel_hi:[1,0]
	v_mul_f32_e32 v129, v129, v4
	v_mov_b32_e32 v3, v2
	v_mov_b32_e32 v4, v2
	v_mov_b32_e32 v5, v2
	v_mov_b32_e32 v6, v2
	v_mov_b32_e32 v7, v2
	v_mov_b32_e32 v8, v2
	v_mov_b32_e32 v9, v2
	v_mov_b32_e32 v10, v2
	v_mov_b32_e32 v11, v2
	v_mov_b32_e32 v12, v2
	v_mov_b32_e32 v13, v2
	v_mov_b32_e32 v14, v2
	v_mov_b32_e32 v15, v2
	v_mov_b32_e32 v16, v2
	v_mov_b32_e32 v17, v2
	s_branch .LBB0_179
